# attention tile loop: two-group ping-pong (waves 4-7 run half a tile behind waves 0-3, two barriers per tile, no setprio)
# baseline (speedup 1.0000x reference)
.LBB0_161:
	v_add3_u32 v96, s10, v110, v142
	ds_read_b128 v[64:67], v96
	ds_read_b128 v[68:71], v96 offset:64
	ds_read_b128 v[72:75], v96 offset:128
	v_mov_b32_e32 v131, v130
	v_mov_b32_e32 v129, v128
	s_waitcnt lgkmcnt(2)
	v_mfma_f32_16x16x32_bf16 v[76:79], v[64:67], v[0:3], 0
	s_mov_b32 s53, s52
	s_mov_b32 s54, s52
	s_mov_b32 s55, s52
	v_mfma_f32_16x16x32_bf16 v[64:67], v[64:67], v[8:11], 0
	v_mov_b32_e32 v127, v157
	s_add_i32 s9, s9, s18
	s_waitcnt lgkmcnt(1)
	v_mfma_f32_16x16x32_bf16 v[76:79], v[68:71], v[4:7], v[76:79]
	v_mfma_f32_16x16x32_bf16 v[64:67], v[68:71], v[12:15], v[64:67]
	s_waitcnt lgkmcnt(0)
	v_mfma_f32_16x16x32_bf16 v[76:79], v[72:75], v[16:19], v[76:79]
	v_mfma_f32_16x16x32_bf16 v[64:67], v[72:75], v[20:23], v[64:67]
	ds_read_b128 v[68:71], v96 offset:3584
	ds_read_b128 v[72:75], v96 offset:3648
	ds_read_b128 v[80:83], v96 offset:3712
	s_waitcnt lgkmcnt(2)
	v_mfma_f32_16x16x32_bf16 v[84:87], v[68:71], v[0:3], 0
	v_mfma_f32_16x16x32_bf16 v[68:71], v[68:71], v[8:11], 0
	s_waitcnt lgkmcnt(1)
	v_mfma_f32_16x16x32_bf16 v[84:87], v[72:75], v[4:7], v[84:87]
	v_mfma_f32_16x16x32_bf16 v[68:71], v[72:75], v[12:15], v[68:71]
	s_waitcnt lgkmcnt(0)
	v_mfma_f32_16x16x32_bf16 v[84:87], v[80:83], v[16:19], v[84:87]
	v_mfma_f32_16x16x32_bf16 v[68:71], v[80:83], v[20:23], v[68:71]
	ds_read_b128 v[72:75], v96 offset:7168
	ds_read_b128 v[80:83], v96 offset:7232
	ds_read_b128 v[88:91], v96 offset:7296
	s_waitcnt lgkmcnt(2)
	v_mfma_f32_16x16x32_bf16 v[92:95], v[72:75], v[0:3], 0
	v_mfma_f32_16x16x32_bf16 v[72:75], v[72:75], v[8:11], 0
	s_waitcnt lgkmcnt(1)
	v_mfma_f32_16x16x32_bf16 v[92:95], v[80:83], v[4:7], v[92:95]
	v_mfma_f32_16x16x32_bf16 v[72:75], v[80:83], v[12:15], v[72:75]
	s_waitcnt lgkmcnt(0)
	v_mfma_f32_16x16x32_bf16 v[92:95], v[88:91], v[16:19], v[92:95]
	v_mfma_f32_16x16x32_bf16 v[72:75], v[88:91], v[20:23], v[72:75]
	ds_read_b128 v[80:83], v96 offset:10752
	ds_read_b128 v[88:91], v96 offset:10816
	ds_read_b128 v[96:99], v96 offset:10880
	s_waitcnt lgkmcnt(2)
	v_mfma_f32_16x16x32_bf16 v[0:3], v[80:83], v[0:3], 0
	s_waitcnt lgkmcnt(1)
	v_mfma_f32_16x16x32_bf16 v[0:3], v[88:91], v[4:7], v[0:3]
	v_mfma_f32_16x16x32_bf16 v[4:7], v[80:83], v[8:11], 0
	v_add_f32_e64 v8, v76, -v130
	v_add_f32_e64 v9, v77, -v131
	v_pk_add_f32 v[10:11], v[78:79], v[130:131] neg_lo:[0,1] neg_hi:[0,1]
	s_waitcnt lgkmcnt(0)
	v_mfma_f32_16x16x32_bf16 v[0:3], v[96:99], v[16:19], v[0:3]
	v_mfma_f32_16x16x32_bf16 v[4:7], v[88:91], v[12:15], v[4:7]
	v_exp_f32_e32 v12, v8
	v_exp_f32_e32 v13, v9
	v_exp_f32_e32 v14, v10
	v_exp_f32_e32 v15, v11
	v_pk_add_f32 v[8:9], v[84:85], v[130:131] neg_lo:[0,1] neg_hi:[0,1]
	v_pk_add_f32 v[10:11], v[86:87], v[130:131] neg_lo:[0,1] neg_hi:[0,1]
	s_nop 0
	v_pk_add_f32 v[0:1], v[0:1], v[130:131] neg_lo:[0,1] neg_hi:[0,1]
	v_pk_add_f32 v[2:3], v[2:3], v[130:131] neg_lo:[0,1] neg_hi:[0,1]
	v_mfma_f32_16x16x32_bf16 v[4:7], v[96:99], v[20:23], v[4:7]
	v_exp_f32_e32 v18, v8
	v_exp_f32_e32 v19, v9
	v_exp_f32_e32 v20, v10
	v_exp_f32_e32 v21, v11
	v_pk_add_f32 v[8:9], v[92:93], v[130:131] neg_lo:[0,1] neg_hi:[0,1]
	v_pk_add_f32 v[10:11], v[94:95], v[130:131] neg_lo:[0,1] neg_hi:[0,1]
	v_exp_f32_e32 v0, v0
	v_exp_f32_e32 v1, v1
	v_exp_f32_e32 v2, v2
	v_exp_f32_e32 v3, v3
	v_exp_f32_e32 v8, v8
	v_exp_f32_e32 v9, v9
	v_exp_f32_e32 v10, v10
	v_exp_f32_e32 v11, v11
	v_cvt_pk_bf16_f32 v16, v12, v13
	v_cvt_pk_bf16_f32 v17, v14, v15
	v_cvt_pk_bf16_f32 v18, v18, v19
	v_cvt_pk_bf16_f32 v19, v20, v21
	v_cvt_pk_bf16_f32 v20, v8, v9
	v_cvt_pk_bf16_f32 v21, v10, v11
	v_cvt_pk_bf16_f32 v22, v0, v1
	v_cvt_pk_bf16_f32 v23, v2, v3
	v_pk_add_f32 v[0:1], v[64:65], v[128:129] neg_lo:[0,1] neg_hi:[0,1]
	v_pk_add_f32 v[2:3], v[66:67], v[128:129] neg_lo:[0,1] neg_hi:[0,1]
	v_exp_f32_e32 v8, v0
	v_exp_f32_e32 v9, v1
	v_exp_f32_e32 v10, v2
	v_exp_f32_e32 v11, v3
	v_pk_add_f32 v[0:1], v[68:69], v[128:129] neg_lo:[0,1] neg_hi:[0,1]
	v_pk_add_f32 v[2:3], v[70:71], v[128:129] neg_lo:[0,1] neg_hi:[0,1]
	v_exp_f32_e32 v12, v0
	v_exp_f32_e32 v13, v1
	v_exp_f32_e32 v14, v2
	v_exp_f32_e32 v15, v3
	v_pk_add_f32 v[0:1], v[72:73], v[128:129] neg_lo:[0,1] neg_hi:[0,1]
	v_pk_add_f32 v[2:3], v[74:75], v[128:129] neg_lo:[0,1] neg_hi:[0,1]
	v_exp_f32_e32 v68, v0
	v_exp_f32_e32 v69, v1
	v_exp_f32_e32 v70, v2
	v_exp_f32_e32 v71, v3
	v_pk_add_f32 v[0:1], v[4:5], v[128:129] neg_lo:[0,1] neg_hi:[0,1]
	v_pk_add_f32 v[2:3], v[6:7], v[128:129] neg_lo:[0,1] neg_hi:[0,1]
	v_add3_u32 v72, s10, v138, v143
	v_exp_f32_e32 v0, v0
	v_exp_f32_e32 v1, v1
	v_exp_f32_e32 v2, v2
	v_exp_f32_e32 v3, v3
	v_cvt_pk_bf16_f32 v64, v8, v9
	v_add_u32_e32 v8, 0x3400, v72
	v_cvt_pk_bf16_f32 v65, v10, v11
	v_cvt_pk_bf16_f32 v66, v12, v13
	v_cvt_pk_bf16_f32 v67, v14, v15
	v_cvt_pk_bf16_f32 v68, v68, v69
	v_cvt_pk_bf16_f32 v69, v70, v71
	v_cvt_pk_bf16_f32 v70, v0, v1
	v_cvt_pk_bf16_f32 v71, v2, v3
	ds_read2_b64 v[0:3], v8 offset0:128 offset1:132
	ds_read2_b64 v[8:11], v8 offset0:136 offset1:140
	s_waitcnt lgkmcnt(1)
	v_mfma_f32_16x16x32_bf16 v[4:7], v[0:3], v[16:19], v[60:63]
	v_add_u32_e32 v12, 0x3c00, v72
	s_lshl_b32 s10, s24, 7
	s_cmp_ge_i32 s9, s19
	v_mfma_f32_16x16x32_bf16 v[0:3], v[0:3], v[64:67], v[56:59]
	s_waitcnt lgkmcnt(0)
	v_mfma_f32_16x16x32_bf16 v[56:59], v[8:11], v[20:23], v[4:7]
	s_nop 2
	ds_read2_b64 v[4:7], v12 offset0:160 offset1:164
	ds_read2_b64 v[12:15], v12 offset0:168 offset1:172
	v_mfma_f32_16x16x32_bf16 v[0:3], v[8:11], v[68:71], v[0:3]
	s_waitcnt lgkmcnt(1)
	v_mfma_f32_16x16x32_bf16 v[8:11], v[4:7], v[16:19], v[52:55]
	s_nop 2
	v_add_u32_e32 v52, 0x4400, v72
	v_mfma_f32_16x16x32_bf16 v[4:7], v[4:7], v[64:67], v[48:51]
	s_waitcnt lgkmcnt(0)
	v_mfma_f32_16x16x32_bf16 v[48:51], v[12:15], v[20:23], v[8:11]
	s_nop 2
	ds_read2_b64 v[8:11], v52 offset0:192 offset1:196
	v_mfma_f32_16x16x32_bf16 v[4:7], v[12:15], v[68:71], v[4:7]
	s_waitcnt lgkmcnt(0)
	v_mfma_f32_16x16x32_bf16 v[12:15], v[8:11], v[16:19], v[44:47]
	v_mfma_f32_16x16x32_bf16 v[8:11], v[8:11], v[64:67], v[40:43]
	s_nop 2
	ds_read2_b64 v[40:43], v52 offset0:200 offset1:204
	s_waitcnt lgkmcnt(0)
	v_mfma_f32_16x16x32_bf16 v[44:47], v[40:43], v[20:23], v[12:15]
	v_mfma_f32_16x16x32_bf16 v[12:15], v[40:43], v[68:71], v[8:11]
	v_add_u32_e32 v40, 0x4c00, v72
	s_nop 1
	ds_read2_b64 v[8:11], v40 offset0:224 offset1:228
	ds_read2_b64 v[40:43], v40 offset0:232 offset1:236
	s_waitcnt lgkmcnt(1)
	v_mfma_f32_16x16x32_bf16 v[36:39], v[8:11], v[16:19], v[36:39]
	s_waitcnt lgkmcnt(0)
	s_barrier
	v_mfma_f32_16x16x32_bf16 v[8:11], v[8:11], v[64:67], v[32:35]
	v_mfma_f32_16x16x32_bf16 v[32:35], v[40:43], v[20:23], v[36:39]
	s_nop 3
	v_mov_b64_e32 v[36:37], s[52:53]
	v_mov_b64_e32 v[38:39], s[54:55]
	v_mfma_f32_16x16x32_bf16 v[8:11], v[40:43], v[68:71], v[8:11]
	s_nop 0
	v_mfma_f32_16x16x32_bf16 v[16:19], v[36:39], v[16:19], v[28:31]
	v_mfma_f32_16x16x32_bf16 v[24:27], v[36:39], v[64:67], v[24:27]
	v_mfma_f32_16x16x32_bf16 v[16:19], v[36:39], v[20:23], v[16:19]
	v_mfma_f32_16x16x32_bf16 v[18:21], v[36:39], v[68:71], v[24:27]
	s_nop 6
	v_div_scale_f32 v17, s[2:3], v16, v16, 1.0
	v_rcp_f32_e32 v19, v17
	v_add_u32_e32 v20, s25, v117
	v_fma_f32 v21, -v17, v19, 1.0
	v_fmac_f32_e32 v19, v21, v19
	v_div_scale_f32 v21, vcc, 1.0, v16, 1.0
	v_mul_f32_e32 v22, v21, v19
	v_fma_f32 v23, -v17, v22, v21
	v_fmac_f32_e32 v22, v23, v19
	v_fma_f32 v17, -v17, v22, v21
	v_ashrrev_i32_e32 v21, 31, v20
	v_div_fmas_f32 v17, v17, v19, v22
	v_lshlrev_b64 v[22:23], 11, v[20:21]
	v_div_fixup_f32 v16, v17, v16, 1.0
	v_lshl_add_u64 v[22:23], s[58:59], 0, v[22:23]
	v_lshl_add_u64 v[22:23], v[22:23], 0, s[10:11]
	v_pk_mul_f32 v[26:27], v[56:57], v[16:17] op_sel_hi:[1,0]
	v_lshl_add_u64 v[22:23], v[22:23], 0, v[126:127]
	v_pk_mul_f32 v[24:25], v[58:59], v[16:17] op_sel_hi:[1,0]
	v_cvt_pk_bf16_f32 v26, v26, v27
	s_nop 0
	v_cvt_pk_bf16_f32 v27, v24, v25
	global_store_dwordx2 v[22:23], v[26:27], off offset:512
	v_pk_mul_f32 v[26:27], v[48:49], v[16:17] op_sel_hi:[1,0]
	v_pk_mul_f32 v[24:25], v[50:51], v[16:17] op_sel_hi:[1,0]
	v_cvt_pk_bf16_f32 v26, v26, v27
	s_nop 0
	v_cvt_pk_bf16_f32 v27, v24, v25
	global_store_dwordx2 v[22:23], v[26:27], off offset:544
	v_pk_mul_f32 v[24:25], v[46:47], v[16:17] op_sel_hi:[1,0]
	v_pk_mul_f32 v[26:27], v[44:45], v[16:17] op_sel_hi:[1,0]
	s_nop 0
	v_cvt_pk_bf16_f32 v26, v26, v27
	v_cvt_pk_bf16_f32 v27, v24, v25
	v_pk_mul_f32 v[24:25], v[34:35], v[16:17] op_sel_hi:[1,0]
	v_pk_mul_f32 v[16:17], v[32:33], v[16:17] op_sel_hi:[1,0]
	global_store_dwordx2 v[22:23], v[26:27], off offset:576
	v_cvt_pk_bf16_f32 v16, v16, v17
	v_cvt_pk_bf16_f32 v17, v24, v25
	global_store_dwordx2 v[22:23], v[16:17], off offset:608
	v_div_scale_f32 v16, s[2:3], v18, v18, 1.0
	v_rcp_f32_e32 v17, v16
	s_nop 0
	v_fma_f32 v19, -v16, v17, 1.0
	v_fmac_f32_e32 v17, v19, v17
	v_div_scale_f32 v19, vcc, 1.0, v18, 1.0
	v_mul_f32_e32 v21, v19, v17
	v_fma_f32 v22, -v16, v21, v19
	v_fmac_f32_e32 v21, v22, v17
	v_fma_f32 v16, -v16, v21, v19
	v_div_fmas_f32 v16, v16, v17, v21
	v_div_fixup_f32 v16, v16, v18, 1.0
	v_add_u32_e32 v18, 16, v20
	v_ashrrev_i32_e32 v19, 31, v18
	v_lshlrev_b64 v[18:19], 11, v[18:19]
	v_lshl_add_u64 v[18:19], s[58:59], 0, v[18:19]
	v_lshl_add_u64 v[18:19], v[18:19], 0, s[10:11]
	v_pk_mul_f32 v[2:3], v[2:3], v[16:17] op_sel_hi:[1,0]
	v_pk_mul_f32 v[0:1], v[0:1], v[16:17] op_sel_hi:[1,0]
	v_lshl_add_u64 v[18:19], v[18:19], 0, v[126:127]
	v_cvt_pk_bf16_f32 v0, v0, v1
	v_cvt_pk_bf16_f32 v1, v2, v3
	v_pk_mul_f32 v[2:3], v[4:5], v[16:17] op_sel_hi:[1,0]
	global_store_dwordx2 v[18:19], v[0:1], off offset:512
	v_pk_mul_f32 v[0:1], v[6:7], v[16:17] op_sel_hi:[1,0]
	v_cvt_pk_bf16_f32 v2, v2, v3
	s_nop 0
	v_cvt_pk_bf16_f32 v3, v0, v1
	global_store_dwordx2 v[18:19], v[2:3], off offset:544
	v_pk_mul_f32 v[2:3], v[12:13], v[16:17] op_sel_hi:[1,0]
	v_pk_mul_f32 v[0:1], v[14:15], v[16:17] op_sel_hi:[1,0]
	v_cvt_pk_bf16_f32 v2, v2, v3
	s_nop 0
	v_cvt_pk_bf16_f32 v3, v0, v1
	global_store_dwordx2 v[18:19], v[2:3], off offset:576
	v_pk_mul_f32 v[2:3], v[8:9], v[16:17] op_sel_hi:[1,0]
	v_pk_mul_f32 v[0:1], v[10:11], v[16:17] op_sel_hi:[1,0]
	v_cvt_pk_bf16_f32 v2, v2, v3
	s_nop 0
	v_cvt_pk_bf16_f32 v3, v0, v1
	global_store_dwordx2 v[18:19], v[2:3], off offset:608
	s_cbranch_scc1 .LBB0_181

.LBB0_173:
	s_or_b64 exec, exec, s[6:7]
	s_add_i32 s6, s34, 1
	s_waitcnt vmcnt(1)
	v_add_u32_e32 v24, 0, v116
	s_add_u32 s34, s21, s35
	v_mov_b32_e32 v26, v157
	v_mov_b32_e32 v27, v157
	s_waitcnt vmcnt(0)
	ds_write_b128 v24, v[28:31] offset:14336
	s_addc_u32 s35, s10, 0
	v_mov_b32_e32 v24, v157
	v_mov_b32_e32 v25, v157
	v_mov_b64_e32 v[30:31], v[26:27]
	v_mov_b64_e32 v[34:35], v[26:27]
	v_mov_b64_e32 v[38:39], v[26:27]
	v_mov_b64_e32 v[42:43], v[26:27]
	v_mov_b64_e32 v[46:47], v[26:27]
	v_mov_b64_e32 v[50:51], v[26:27]
	v_mov_b64_e32 v[54:55], v[26:27]
	v_mov_b64_e32 v[58:59], v[26:27]
	v_mov_b64_e32 v[62:63], v[26:27]
	v_lshl_add_u64 v[132:133], v[120:121], 0, s[34:35]
	v_lshl_add_u64 v[134:135], v[122:123], 0, s[2:3]
	v_lshl_add_u64 v[136:137], v[124:125], 0, s[2:3]
	s_mov_b32 s7, 0
	v_mov_b32_e32 v128, 0xf149f2ca
	v_mov_b64_e32 v[28:29], v[24:25]
	v_mov_b64_e32 v[32:33], v[24:25]
	v_mov_b64_e32 v[36:37], v[24:25]
	v_mov_b64_e32 v[40:41], v[24:25]
	v_mov_b64_e32 v[44:45], v[24:25]
	v_mov_b64_e32 v[48:49], v[24:25]
	v_mov_b64_e32 v[52:53], v[24:25]
	v_mov_b64_e32 v[56:57], v[24:25]
	v_mov_b64_e32 v[60:61], v[24:25]
	v_mov_b32_e32 v130, 0xf149f2ca
	s_waitcnt lgkmcnt(0)
	v_mov_b32_e32 v250, s52
	v_mov_b32_e32 v251, s52
	v_mov_b32_e32 v252, s52
	v_mov_b32_e32 v253, s52
	v_add_u32_e32 v104, v110, v142
	v_add_u32_e32 v147, v138, v143
	v_readfirstlane_b32 s2, v160
	s_cmpk_ge_u32 s2, 0x100
	s_cbranch_scc1 .LattnB_entry
	s_branch .LBB0_175

.Lattn_sm:
	s_barrier
	v_exp_f32_e32 v92, v92
	v_exp_f32_e32 v93, v93
	v_exp_f32_e32 v94, v94
	v_exp_f32_e32 v95, v95
	v_exp_f32_e32 v96, v96
	v_exp_f32_e32 v97, v97
	v_exp_f32_e32 v98, v98
	v_exp_f32_e32 v99, v99
	v_exp_f32_e32 v100, v100
	v_exp_f32_e32 v101, v101
	v_exp_f32_e32 v102, v102
	v_exp_f32_e32 v103, v103
	v_exp_f32_e32 v104, v104
	v_exp_f32_e32 v105, v105
	v_exp_f32_e32 v106, v106
	v_exp_f32_e32 v107, v107
	v_cvt_pk_bf16_f32 v92, v92, v93
	v_cvt_pk_bf16_f32 v93, v94, v95
	v_cvt_pk_bf16_f32 v94, v96, v97
	v_cvt_pk_bf16_f32 v95, v98, v99
	v_cvt_pk_bf16_f32 v96, v100, v101
	v_cvt_pk_bf16_f32 v97, v102, v103
	v_cvt_pk_bf16_f32 v98, v104, v105
	v_cvt_pk_bf16_f32 v99, v106, v107
	v_exp_f32_e32 v76, v76
	v_exp_f32_e32 v77, v77
	v_exp_f32_e32 v78, v78
	v_exp_f32_e32 v79, v79
	v_exp_f32_e32 v80, v80
	v_exp_f32_e32 v81, v81
	v_exp_f32_e32 v82, v82
	v_exp_f32_e32 v83, v83
	v_exp_f32_e32 v84, v84
	v_exp_f32_e32 v85, v85
	v_exp_f32_e32 v86, v86
	v_exp_f32_e32 v87, v87
	v_exp_f32_e32 v88, v88
	v_exp_f32_e32 v89, v89
	v_exp_f32_e32 v90, v90
	v_exp_f32_e32 v91, v91
	v_cvt_pk_bf16_f32 v76, v76, v77
	v_cvt_pk_bf16_f32 v77, v78, v79
	v_cvt_pk_bf16_f32 v78, v80, v81
	v_cvt_pk_bf16_f32 v79, v82, v83
	v_cvt_pk_bf16_f32 v80, v84, v85
	v_cvt_pk_bf16_f32 v81, v86, v87
	v_cvt_pk_bf16_f32 v82, v88, v89
	v_cvt_pk_bf16_f32 v83, v90, v91
	s_add_i32 s7, s7, 1
	s_bitcmp1_b32 s7, 0
	s_cselect_b32 s2, 0x5c00, 0
	s_add_i32 s10, s2, 0
	v_add_u32_e32 v127, s10, v139
	v_add_u32_e32 v129, s10, v140
	v_add_u32_e32 v131, s10, v116
	s_waitcnt vmcnt(2)
	ds_write_b128 v127, v[72:75]
	s_waitcnt vmcnt(0)
	ds_write_b128 v131, v[64:67] offset:14336
	s_and_b64 vcc, exec, s[42:43]
	s_cbranch_vccz .Lattn_skipw
	ds_write_b128 v129, v[68:71]

.LattnB_entry:
	s_barrier
	global_load_dwordx4 v[72:75], v[136:137], off
	global_load_dwordx4 v[68:71], v[134:135], off
	global_load_dwordx4 v[64:67], v[132:133], off
	v_lshl_add_u64 v[132:133], v[132:133], 0, s[50:51]
	v_lshl_add_u64 v[134:135], v[134:135], 0, s[4:5]
	v_lshl_add_u64 v[136:137], v[136:137], 0, s[4:5]
	s_barrier
.LattnB_loop:
	ds_read_b128 v[162:165], v104
	ds_read_b128 v[166:169], v104 offset:64
	ds_read_b128 v[170:173], v104 offset:128
	ds_read_b128 v[174:177], v104 offset:3584
	ds_read_b128 v[178:181], v104 offset:3648
	ds_read_b128 v[182:185], v104 offset:3712
	ds_read_b128 v[186:189], v104 offset:7168
	ds_read_b128 v[214:217], v104 offset:7232
	ds_read_b128 v[218:221], v104 offset:7296
	ds_read_b128 v[222:225], v104 offset:10752
	ds_read_b128 v[226:229], v104 offset:10816
	ds_read_b128 v[230:233], v104 offset:10880
	s_and_b32 s21, s7, 15
	s_cbranch_scc0 .LattnB_refresh
	s_waitcnt lgkmcnt(11)
	v_mfma_f32_16x16x32_bf16 v[92:95], v[162:165], v[0:3], v[148:151]
	v_mfma_f32_16x16x32_bf16 v[76:79], v[162:165], v[8:11], v[152:155]
	ds_read_b64 v[234:235], v147 offset:14336
	ds_read_b64 v[236:237], v147 offset:14368
	s_waitcnt lgkmcnt(12)
	v_mfma_f32_16x16x32_bf16 v[92:95], v[166:169], v[4:7], v[92:95]
	v_mfma_f32_16x16x32_bf16 v[76:79], v[166:169], v[12:15], v[76:79]
	ds_read_b64 v[238:239], v147 offset:14400
	ds_read_b64 v[240:241], v147 offset:14432
	s_waitcnt lgkmcnt(13)
	v_mfma_f32_16x16x32_bf16 v[92:95], v[170:173], v[16:19], v[92:95]
	v_mfma_f32_16x16x32_bf16 v[76:79], v[170:173], v[20:23], v[76:79]
	ds_read_b64 v[242:243], v147 offset:16640
	ds_read_b64 v[244:245], v147 offset:16672
	s_waitcnt lgkmcnt(14)
	v_mfma_f32_16x16x32_bf16 v[96:99], v[174:177], v[0:3], v[148:151]
	v_mfma_f32_16x16x32_bf16 v[80:83], v[174:177], v[8:11], v[152:155]
	ds_read_b64 v[246:247], v147 offset:16704
	s_waitcnt lgkmcnt(14)
	v_mfma_f32_16x16x32_bf16 v[96:99], v[178:181], v[4:7], v[96:99]
	v_mfma_f32_16x16x32_bf16 v[80:83], v[178:181], v[12:15], v[80:83]
	ds_read_b64 v[248:249], v147 offset:16736
	s_waitcnt lgkmcnt(14)
	v_mfma_f32_16x16x32_bf16 v[96:99], v[182:185], v[16:19], v[96:99]
	v_mfma_f32_16x16x32_bf16 v[80:83], v[182:185], v[20:23], v[80:83]
	ds_read_b64 v[162:163], v147 offset:18944
	s_waitcnt lgkmcnt(14)
	v_mfma_f32_16x16x32_bf16 v[100:103], v[186:189], v[0:3], v[148:151]
	v_mfma_f32_16x16x32_bf16 v[84:87], v[186:189], v[8:11], v[152:155]
	ds_read_b64 v[164:165], v147 offset:18976
	s_waitcnt lgkmcnt(14)
	v_mfma_f32_16x16x32_bf16 v[100:103], v[214:217], v[4:7], v[100:103]
	v_mfma_f32_16x16x32_bf16 v[84:87], v[214:217], v[12:15], v[84:87]
	ds_read_b64 v[166:167], v147 offset:19008
	s_waitcnt lgkmcnt(14)
	v_mfma_f32_16x16x32_bf16 v[100:103], v[218:221], v[16:19], v[100:103]
	v_mfma_f32_16x16x32_bf16 v[84:87], v[218:221], v[20:23], v[84:87]
	ds_read_b64 v[168:169], v147 offset:19040
	s_waitcnt lgkmcnt(14)
	v_mfma_f32_16x16x32_bf16 v[104:107], v[222:225], v[0:3], v[148:151]
	v_mfma_f32_16x16x32_bf16 v[88:91], v[222:225], v[8:11], v[152:155]
	ds_read_b64 v[170:171], v147 offset:21248
	s_waitcnt lgkmcnt(14)
	v_mfma_f32_16x16x32_bf16 v[104:107], v[226:229], v[4:7], v[104:107]
	v_mfma_f32_16x16x32_bf16 v[88:91], v[226:229], v[12:15], v[88:91]
	ds_read_b64 v[172:173], v147 offset:21280
	s_waitcnt lgkmcnt(14)
	v_mfma_f32_16x16x32_bf16 v[104:107], v[230:233], v[16:19], v[104:107]
	v_mfma_f32_16x16x32_bf16 v[88:91], v[230:233], v[20:23], v[88:91]
	s_waitcnt lgkmcnt(13)
	ds_read_b64 v[174:175], v147 offset:21312
	ds_read_b64 v[176:177], v147 offset:21344
.LattnB_w:
	s_add_i32 s7, s7, 1
	s_bitcmp1_b32 s7, 0
	s_cselect_b32 s2, 0x5c00, 0
	s_add_i32 s10, s2, 0
	v_add_u32_e32 v127, s10, v139
	v_add_u32_e32 v129, s10, v140
	v_add_u32_e32 v131, s10, v116
	s_waitcnt vmcnt(2)
	ds_write_b128 v127, v[72:75]
	s_waitcnt vmcnt(0)
	ds_write_b128 v131, v[64:67] offset:14336
	s_and_b64 vcc, exec, s[42:43]
	s_cbranch_vccz .LattnB_skipw
	ds_write_b128 v129, v[68:71]
.LattnB_skipw:
	s_waitcnt lgkmcnt(0)
	s_barrier
	s_cmp_eq_u32 s6, s7
	s_cbranch_scc1 .LattnB_last
	global_load_dwordx4 v[72:75], v[136:137], off
	global_load_dwordx4 v[68:71], v[134:135], off
	global_load_dwordx4 v[64:67], v[132:133], off
	v_lshl_add_u64 v[132:133], v[132:133], 0, s[50:51]
	v_lshl_add_u64 v[134:135], v[134:135], 0, s[4:5]
	v_lshl_add_u64 v[136:137], v[136:137], 0, s[4:5]
	v_exp_f32_e32 v92, v92
	v_exp_f32_e32 v93, v93
	v_exp_f32_e32 v94, v94
	v_exp_f32_e32 v95, v95
	v_exp_f32_e32 v96, v96
	v_exp_f32_e32 v97, v97
	v_exp_f32_e32 v98, v98
	v_exp_f32_e32 v99, v99
	v_exp_f32_e32 v100, v100
	v_exp_f32_e32 v101, v101
	v_exp_f32_e32 v102, v102
	v_exp_f32_e32 v103, v103
	v_exp_f32_e32 v104, v104
	v_exp_f32_e32 v105, v105
	v_exp_f32_e32 v106, v106
	v_exp_f32_e32 v107, v107
	v_cvt_pk_bf16_f32 v92, v92, v93
	v_cvt_pk_bf16_f32 v93, v94, v95
	v_cvt_pk_bf16_f32 v94, v96, v97
	v_cvt_pk_bf16_f32 v95, v98, v99
	v_cvt_pk_bf16_f32 v96, v100, v101
	v_cvt_pk_bf16_f32 v97, v102, v103
	v_cvt_pk_bf16_f32 v98, v104, v105
	v_cvt_pk_bf16_f32 v99, v106, v107
	v_exp_f32_e32 v76, v76
	v_exp_f32_e32 v77, v77
	v_exp_f32_e32 v78, v78
	v_exp_f32_e32 v79, v79
	v_exp_f32_e32 v80, v80
	v_exp_f32_e32 v81, v81
	v_exp_f32_e32 v82, v82
	v_exp_f32_e32 v83, v83
	v_exp_f32_e32 v84, v84
	v_exp_f32_e32 v85, v85
	v_exp_f32_e32 v86, v86
	v_exp_f32_e32 v87, v87
	v_exp_f32_e32 v88, v88
	v_exp_f32_e32 v89, v89
	v_exp_f32_e32 v90, v90
	v_exp_f32_e32 v91, v91
	v_cvt_pk_bf16_f32 v76, v76, v77
	v_cvt_pk_bf16_f32 v77, v78, v79
	v_cvt_pk_bf16_f32 v78, v80, v81
	v_cvt_pk_bf16_f32 v79, v82, v83
	v_cvt_pk_bf16_f32 v80, v84, v85
	v_cvt_pk_bf16_f32 v81, v86, v87
	v_cvt_pk_bf16_f32 v82, v88, v89
	v_cvt_pk_bf16_f32 v83, v90, v91
	s_nop 1
	v_mfma_f32_16x16x32_bf16 v[60:63], v[234:237], v[92:95], v[60:63]
	v_mfma_f32_16x16x32_bf16 v[56:59], v[234:237], v[76:79], v[56:59]
	v_mfma_f32_16x16x32_bf16 v[60:63], v[238:241], v[96:99], v[60:63]
	v_mfma_f32_16x16x32_bf16 v[56:59], v[238:241], v[80:83], v[56:59]
	v_mfma_f32_16x16x32_bf16 v[52:55], v[242:245], v[92:95], v[52:55]
	v_mfma_f32_16x16x32_bf16 v[48:51], v[242:245], v[76:79], v[48:51]
	v_mfma_f32_16x16x32_bf16 v[52:55], v[246:249], v[96:99], v[52:55]
	v_mfma_f32_16x16x32_bf16 v[48:51], v[246:249], v[80:83], v[48:51]
	v_mfma_f32_16x16x32_bf16 v[44:47], v[162:165], v[92:95], v[44:47]
	v_mfma_f32_16x16x32_bf16 v[40:43], v[162:165], v[76:79], v[40:43]
	v_mfma_f32_16x16x32_bf16 v[44:47], v[166:169], v[96:99], v[44:47]
	v_mfma_f32_16x16x32_bf16 v[40:43], v[166:169], v[80:83], v[40:43]
	v_mfma_f32_16x16x32_bf16 v[36:39], v[170:173], v[92:95], v[36:39]
	v_mfma_f32_16x16x32_bf16 v[32:35], v[170:173], v[76:79], v[32:35]
	v_mfma_f32_16x16x32_bf16 v[36:39], v[174:177], v[96:99], v[36:39]
	v_mfma_f32_16x16x32_bf16 v[32:35], v[174:177], v[80:83], v[32:35]
	v_mfma_f32_16x16x32_bf16 v[28:31], v[250:253], v[92:95], v[28:31]
	v_mfma_f32_16x16x32_bf16 v[24:27], v[250:253], v[76:79], v[24:27]
	v_mfma_f32_16x16x32_bf16 v[28:31], v[250:253], v[96:99], v[28:31]
	v_mfma_f32_16x16x32_bf16 v[24:27], v[250:253], v[80:83], v[24:27]
	v_add3_u32 v104, s10, v110, v142
	v_add3_u32 v147, s10, v138, v143
	s_barrier
	s_branch .LattnB_loop
.LattnB_last:
	v_exp_f32_e32 v92, v92
	v_exp_f32_e32 v93, v93
	v_exp_f32_e32 v94, v94
	v_exp_f32_e32 v95, v95
	v_exp_f32_e32 v96, v96
	v_exp_f32_e32 v97, v97
	v_exp_f32_e32 v98, v98
	v_exp_f32_e32 v99, v99
	v_exp_f32_e32 v100, v100
	v_exp_f32_e32 v101, v101
	v_exp_f32_e32 v102, v102
	v_exp_f32_e32 v103, v103
	v_exp_f32_e32 v104, v104
	v_exp_f32_e32 v105, v105
	v_exp_f32_e32 v106, v106
	v_exp_f32_e32 v107, v107
	v_cvt_pk_bf16_f32 v92, v92, v93
	v_cvt_pk_bf16_f32 v93, v94, v95
	v_cvt_pk_bf16_f32 v94, v96, v97
	v_cvt_pk_bf16_f32 v95, v98, v99
	v_cvt_pk_bf16_f32 v96, v100, v101
	v_cvt_pk_bf16_f32 v97, v102, v103
	v_cvt_pk_bf16_f32 v98, v104, v105
	v_cvt_pk_bf16_f32 v99, v106, v107
	v_exp_f32_e32 v76, v76
	v_exp_f32_e32 v77, v77
	v_exp_f32_e32 v78, v78
	v_exp_f32_e32 v79, v79
	v_exp_f32_e32 v80, v80
	v_exp_f32_e32 v81, v81
	v_exp_f32_e32 v82, v82
	v_exp_f32_e32 v83, v83
	v_exp_f32_e32 v84, v84
	v_exp_f32_e32 v85, v85
	v_exp_f32_e32 v86, v86
	v_exp_f32_e32 v87, v87
	v_exp_f32_e32 v88, v88
	v_exp_f32_e32 v89, v89
	v_exp_f32_e32 v90, v90
	v_exp_f32_e32 v91, v91
	v_cvt_pk_bf16_f32 v76, v76, v77
	v_cvt_pk_bf16_f32 v77, v78, v79
	v_cvt_pk_bf16_f32 v78, v80, v81
	v_cvt_pk_bf16_f32 v79, v82, v83
	v_cvt_pk_bf16_f32 v80, v84, v85
	v_cvt_pk_bf16_f32 v81, v86, v87
	v_cvt_pk_bf16_f32 v82, v88, v89
	v_cvt_pk_bf16_f32 v83, v90, v91
	s_nop 1
	v_mfma_f32_16x16x32_bf16 v[60:63], v[234:237], v[92:95], v[60:63]
	v_mfma_f32_16x16x32_bf16 v[56:59], v[234:237], v[76:79], v[56:59]
	v_mfma_f32_16x16x32_bf16 v[60:63], v[238:241], v[96:99], v[60:63]
	v_mfma_f32_16x16x32_bf16 v[56:59], v[238:241], v[80:83], v[56:59]
	v_mfma_f32_16x16x32_bf16 v[52:55], v[242:245], v[92:95], v[52:55]
	v_mfma_f32_16x16x32_bf16 v[48:51], v[242:245], v[76:79], v[48:51]
	v_mfma_f32_16x16x32_bf16 v[52:55], v[246:249], v[96:99], v[52:55]
	v_mfma_f32_16x16x32_bf16 v[48:51], v[246:249], v[80:83], v[48:51]
	v_mfma_f32_16x16x32_bf16 v[44:47], v[162:165], v[92:95], v[44:47]
	v_mfma_f32_16x16x32_bf16 v[40:43], v[162:165], v[76:79], v[40:43]
	v_mfma_f32_16x16x32_bf16 v[44:47], v[166:169], v[96:99], v[44:47]
	v_mfma_f32_16x16x32_bf16 v[40:43], v[166:169], v[80:83], v[40:43]
	v_mfma_f32_16x16x32_bf16 v[36:39], v[170:173], v[92:95], v[36:39]
	v_mfma_f32_16x16x32_bf16 v[32:35], v[170:173], v[76:79], v[32:35]
	v_mfma_f32_16x16x32_bf16 v[36:39], v[174:177], v[96:99], v[36:39]
	v_mfma_f32_16x16x32_bf16 v[32:35], v[174:177], v[80:83], v[32:35]
	v_mfma_f32_16x16x32_bf16 v[28:31], v[250:253], v[92:95], v[28:31]
	v_mfma_f32_16x16x32_bf16 v[24:27], v[250:253], v[76:79], v[24:27]
	v_mfma_f32_16x16x32_bf16 v[28:31], v[250:253], v[96:99], v[28:31]
	v_mfma_f32_16x16x32_bf16 v[24:27], v[250:253], v[80:83], v[24:27]
	s_nop 7
	s_nop 7
	s_branch .LBB0_161
